# mix item loop: static re-schedule by halves (vblocks <256: scan + 4 window-attn items; >=256: 4 neighbourhood-attn items + ctx)
# baseline (speedup 1.0000x reference)
; DI void mix_phase(const Params& p, int layer, unsigned char* smem, unsigned char* smem_all, int bid, int nb, int rrank) {
;     ...
;   for (int it = 2 * rrank + (bid & 1); it < e6; it += nb) {
;     if (it < e0) scan_item(p, it);
;     else if (it < e1) {
;     } else if (it < e2) {
;     } else if (it < e3) {
;       const int j = it - e2, qb = j & 127, hq = (j >> 7) & 3, b = j >> 9;
;       const int t0 = qb * 128 + wave * 32;
;       attn64_wave<1>(p, layer, b, hq, b * SEQ + t0, t0, rpb_lds, smem + 8192 + wave * W64_BYTES);
;     } else if (it < e4) {
;       const int j = it - e3, qb = j & 127, hq = (j >> 7) & 3, b = j >> 9;
;       const int t0 = qb * 128 + wave * 32;
;       attn64_wave<0>(p, layer, b, hq, b * SEQ + t0, t0, rpb_lds, smem + 8192 + wave * W64_BYTES);
;     } else if (it < e5) {
;       const int j = it - e4, qb = j & 1, hq = (j >> 1) & 3, b = j >> 3;
;       attn64_wave<3>(p, layer, b, hq, TL + b * CTX + qb * 128 + wave * 32, 0, rpb_lds, smem + 8192 + wave * W64_BYTES);
;     } else {
;       const int j = it - e5, qb = j & 1, hq = (j >> 1) & 3, b = j >> 3;
;       attn64_wave<2>(p, layer, b, hq, TL + b * CTX + qb * 128 + wave * 32, 0, rpb_lds, smem + 8192 + wave * W64_BYTES);
;     }
;   }
.LBB0_319:
	s_or_b64 exec, exec, s[2:3]
	s_and_b64 s[2:3], s[42:43], exec
	s_cselect_b32 s2, 16, 0
	s_or_b32 s3, s2, 0xd00
	s_add_i32 s21, s3, s2
	v_writelane_b32 v254, s3, 60
	s_add_i32 s22, s21, s2
	v_readlane_b32 s3, v253, 49
	v_writelane_b32 v254, s22, 61
	s_cmp_ge_i32 s3, s22
	s_waitcnt lgkmcnt(0)
	s_barrier
	s_cbranch_scc1 .LBB0_436
	v_writelane_b32 v254, s21, 62
	v_ashrrev_i32_e32 v0, 6, v238
	s_movk_i32 s3, 0x2600
	v_readlane_b32 s24, v254, 52
	s_waitcnt vmcnt(16)
	v_lshlrev_b32_e32 v152, 5, v0
	v_mul_lo_u32 v0, v0, s3
	s_lshl_b32 s3, s24, 2
	v_readlane_b32 s25, v254, 53
	v_writelane_b32 v254, s3, 63
	s_lshl_b32 s22, s24, 6
	v_readlane_b32 s40, v254, 18
	s_or_b32 s27, s2, 0x500
	s_or_b32 s48, s2, 0x900
	s_lshl_b64 s[24:25], s[22:23], 2
	v_readlane_b32 s42, v254, 20
	v_readlane_b32 s43, v254, 21
	s_add_u32 s28, s42, s24
	s_addc_u32 s29, s43, s25
	v_readlane_b32 s44, v254, 22
	v_writelane_b32 v255, s28, 0
	v_readlane_b32 s45, v254, 23
	v_readlane_b32 s21, v253, 44
	v_writelane_b32 v255, s29, 1
	s_add_u32 s28, s44, s24
	s_addc_u32 s29, s45, s25
	v_writelane_b32 v255, s28, 2
	v_add_u32_e32 v153, s90, v0
	v_and_b32_e32 v154, 32, v152
	v_writelane_b32 v255, s29, 3
	v_readlane_b32 s28, v254, 6
	v_readlane_b32 s29, v254, 7
	s_add_u32 s28, s28, s24
	v_readlane_b32 s30, v254, 8
	s_addc_u32 s29, s29, s25
	v_readlane_b32 s31, v254, 9
	v_writelane_b32 v255, s28, 4
	s_add_u32 s24, s30, s24
	s_addc_u32 s25, s31, s25
	v_writelane_b32 v255, s29, 5
	v_writelane_b32 v255, s24, 6
	s_lshl_b32 s3, s2, 1
	s_sub_i32 s21, s21, s3
	v_writelane_b32 v255, s25, 7
	v_readlane_b32 s3, v253, 50
	s_sub_i32 s2, s3, s2
	v_writelane_b32 v255, s27, 8
	s_lshl_b32 s38, s2, 7
	v_readlane_b32 s39, v253, 57
	v_readlane_b32 s40, v253, 49
	v_writelane_b32 v255, s48, 9
	v_readlane_b32 s41, v254, 19
	v_readlane_b32 s46, v254, 24
	v_readlane_b32 s47, v254, 25
	s_add_i32 s2, s48, 0xffffff00
	s_cmpk_lt_i32 s40, 0x100
	s_cselect_b32 s2, 0, s2
	s_add_i32 s40, s40, s2
	s_add_i32 s21, s21, s2
	s_lshl_b32 s3, s2, 7
	s_add_i32 s38, s38, s3
	s_lshl_b32 s3, s2, 8
	s_add_i32 s39, s39, s3
	s_branch .LBB0_322
